# combo24: combo23 + chunk-attention: far-tile body issues all 8 K-fragment LDS reads at its top; the common PV part issues the first 8 V-fragment reads in its leading wait slot (replacing s_nop 6) into
# speedup vs baseline: 1.0093x; 1.0031x over previous
; #define LAS __attribute__((address_space(3)))
; __device__ __forceinline__ unsigned pk2(float lo, float hi) { f32x2_t v = {lo, hi}; bf16x2_t b = __builtin_convertvector(v, bf16x2_t); return __builtin_bit_cast(unsigned, b); }
; #define MFMA32(a, b, c) __builtin_amdgcn_mfma_f32_32x32x16_bf16((a), (b), (c), 0, 0, 0)
; __device__ __forceinline__ s16x4 vtr(const LAS unsigned char* p) { return __builtin_bit_cast(s16x4, __builtin_amdgcn_ds_read_tr16_b64_v4i16((LAS v4i16_t*)p)); }
; template <int TYPE> __device__ __forceinline__ void attn_unit(const AttnCtx& C, int b, int h, int qb, LAS unsigned char* lds, int tid_in, unsigned* counter) {
;     ...
;                 f32x2_t a2 = {0.f, 0.f};
; #pragma unroll
;                 for (int r = 0; r < 16; r += 2) { a2 += (f32x2_t){p0[r], p0[r + 1]}; a2 += (f32x2_t){p1[r], p1[r + 1]}; }
;                 lsum += a2[0] + a2[1];
;                 bf16x8 pa[4];
; #pragma unroll
;                 for (int s = 0; s < 2; ++s) {
;                     u32x4 a, c2;
;                     a.x = pk2(p0[8 * s + 0], p0[8 * s + 1]); a.y = pk2(p0[8 * s + 2], p0[8 * s + 3]); a.z = pk2(p0[8 * s + 4], p0[8 * s + 5]); a.w = pk2(p0[8 * s + 6], p0[8 * s + 7]);
;                     c2.x = pk2(p1[8 * s + 0], p1[8 * s + 1]); c2.y = pk2(p1[8 * s + 2], p1[8 * s + 3]); c2.z = pk2(p1[8 * s + 4], p1[8 * s + 5]); c2.w = pk2(p1[8 * s + 6], p1[8 * s + 7]);
;                     pa[s] = __builtin_bit_cast(bf16x8, a); pa[2 + s] = __builtin_bit_cast(bf16x8, c2);
;                 }
;                 const LAS unsigned char* vp = Vb + bo + vb0;
; #pragma unroll
;                 for (int dh = 0; dh < 2; ++dh)
; #pragma unroll
;                     for (int ks = 0; ks < 4; ++ks) {
;                         const s16x4 lo = vtr(vp + dh * 4096 + ks * 1024), hh = vtr(vp + dh * 4096 + ks * 1024 + 512);
;                         const bf16x8 vf = {lo[0], lo[1], lo[2], lo[3], hh[0], hh[1], hh[2], hh[3]};
;                         o[dh] = MFMA32(pa[ks], vf, o[dh]);
;                     }
.LBB0_384:
	v_add_u32_e32 v248, s16, v137
	ds_read_b64_tr_b16 v[232:233], v248 offset:32768
	ds_read_b64_tr_b16 v[234:235], v248 offset:33280
	ds_read_b64_tr_b16 v[236:237], v248 offset:33792
	ds_read_b64_tr_b16 v[238:239], v248 offset:34304
	ds_read_b64_tr_b16 v[240:241], v248 offset:34816
	ds_read_b64_tr_b16 v[242:243], v248 offset:35328
	ds_read_b64_tr_b16 v[244:245], v248 offset:35840
	ds_read_b64_tr_b16 v[246:247], v248 offset:36352
	v_add_u32_e32 v88, s16, v137
	s_nop 0
	v_cvt_pk_bf16_f32 v64, v32, v33
	v_cvt_pk_bf16_f32 v65, v34, v35
	v_cvt_pk_bf16_f32 v66, v36, v37
	v_cvt_pk_bf16_f32 v67, v38, v39
	s_waitcnt lgkmcnt(0)
	s_nop 0
	v_mfma_f32_32x32x16_bf16 v[0:15], v[64:67], v[232:235], v[0:15]
	v_cvt_pk_bf16_f32 v72, v40, v41
	v_cvt_pk_bf16_f32 v73, v42, v43
	v_cvt_pk_bf16_f32 v74, v44, v45
	v_cvt_pk_bf16_f32 v75, v46, v47
	v_cvt_pk_bf16_f32 v68, v48, v49
	v_cvt_pk_bf16_f32 v69, v50, v51
	s_waitcnt lgkmcnt(0)
	v_mfma_f32_32x32x16_bf16 v[0:15], v[72:75], v[236:239], v[0:15]
	v_cvt_pk_bf16_f32 v70, v52, v53
	v_cvt_pk_bf16_f32 v71, v54, v55
	v_exp_f32_e32 v63, v63
	v_cvt_pk_bf16_f32 v80, v56, v57
	v_cvt_pk_bf16_f32 v81, v58, v59
	s_waitcnt lgkmcnt(2)
	v_mfma_f32_32x32x16_bf16 v[0:15], v[68:71], v[240:243], v[0:15]
	ds_read_b64_tr_b16 v[76:77], v88 offset:36864
	ds_read_b64_tr_b16 v[78:79], v88 offset:37376
	v_cvt_pk_bf16_f32 v82, v60, v61
	v_cvt_pk_bf16_f32 v83, v62, v63
	v_add_f32_e64 v32, v32, 0
	v_add_f32_e64 v33, v33, 0
	v_pk_add_f32 v[32:33], v[48:49], v[32:33]
	s_waitcnt lgkmcnt(0)
	v_mfma_f32_32x32x16_bf16 v[16:31], v[64:67], v[76:79], v[16:31]
	v_add_f32_e64 v32, v34, v32
	v_add_f32_e64 v33, v35, v33
	v_add_f32_e64 v32, v50, v32
	v_add_f32_e64 v33, v51, v33
	v_add_f32_e64 v32, v36, v32
	v_add_f32_e64 v33, v37, v33
	v_pk_add_f32 v[32:33], v[52:53], v[32:33]
	v_mfma_f32_32x32x16_bf16 v[0:15], v[80:83], v[244:247], v[0:15]
	ds_read_b64_tr_b16 v[84:85], v88 offset:37888
	ds_read_b64_tr_b16 v[86:87], v88 offset:38400
	v_add_f32_e64 v32, v38, v32
	v_add_f32_e64 v33, v39, v33
	v_add_f32_e64 v32, v54, v32
	v_add_f32_e64 v33, v55, v33
	v_pk_add_f32 v[36:37], v[40:41], v[32:33]
	ds_read_b64_tr_b16 v[32:33], v88 offset:38912
	ds_read_b64_tr_b16 v[34:35], v88 offset:39424
	s_waitcnt lgkmcnt(2)
	v_mfma_f32_32x32x16_bf16 v[16:31], v[72:75], v[84:87], v[16:31]
	v_add_f32_e64 v36, v56, v36
	v_add_f32_e64 v37, v57, v37
	v_add_f32_e64 v40, v42, v36
	v_add_f32_e64 v41, v43, v37
	ds_read_b64_tr_b16 v[36:37], v88 offset:39936
	ds_read_b64_tr_b16 v[38:39], v88 offset:40448
	s_waitcnt lgkmcnt(2)
	v_mfma_f32_32x32x16_bf16 v[16:31], v[68:71], v[32:35], v[16:31]
	v_add_f32_e64 v32, v58, v40
	v_add_f32_e64 v33, v59, v41
	v_add_f32_e64 v32, v44, v32
	v_add_f32_e64 v33, v45, v33
	v_add_f32_e64 v32, v60, v32
	v_add_f32_e64 v33, v61, v33
	v_pk_add_f32 v[32:33], v[46:47], v[32:33]
	s_waitcnt lgkmcnt(0)
	v_mfma_f32_32x32x16_bf16 v[16:31], v[80:83], v[36:39], v[16:31]
	v_add_f32_e64 v32, v62, v32
	v_add_f32_e64 v33, v63, v33
	v_add_f32_e32 v32, v32, v33
	v_add_f32_e32 v138, v138, v32

; #define LAS __attribute__((address_space(3)))
; __device__ __forceinline__ float fast_exp2(float x) { return __builtin_amdgcn_exp2f(x); }
; #define MFMA32(a, b, c) __builtin_amdgcn_mfma_f32_32x32x16_bf16((a), (b), (c), 0, 0, 0)
; template <int TYPE> __device__ __forceinline__ void attn_unit(const AttnCtx& C, int b, int h, int qb, LAS unsigned char* lds, int tid_in, unsigned* counter) {
;     ...
;                 const LAS unsigned char* kp = Kb + bo + hi * 1024 + r32 * 16;
; #pragma unroll
;                 for (int d0 = 0; d0 < 4; ++d0) {
;                     const bf16x8 a0 = *(const LAS bf16x8*)(kp + d0 * 2048), a1 = *(const LAS bf16x8*)(kp + d0 * 2048 + 512);
;                     if (d0 == 0) { p0 = MFMA32(a0, qr[0], (TYPE == 1 ? cvec : zvec)); p1 = MFMA32(a1, qr[0], (TYPE == 1 ? cvec : zvec)); }
;                     else { p0 = MFMA32(a0, qr[d0], p0); p1 = MFMA32(a1, qr[d0], p1); }
;                 }
;     ...
;                     if (cq - t >= 3) { const float bc = relb[256];
; #pragma unroll
;                         for (int r = 0; r < 16; ++r) { p0[r] = fast_exp2(p0[r] + bc); p1[r] = fast_exp2(p1[r] + bc); }
.Lt2far_1:
	v_add_u32_e32 v40, s16, v139
	ds_read_b128 v[32:35], v40
	ds_read_b128 v[36:39], v40 offset:512
	ds_read_b128 v[44:47], v40 offset:2048
	ds_read_b128 v[48:51], v40 offset:2560
	ds_read_b128 v[52:55], v40 offset:4096
	ds_read_b128 v[56:59], v40 offset:4608
	ds_read_b128 v[60:63], v40 offset:6144
	ds_read_b128 v[146:149], v40 offset:6656
	s_waitcnt vmcnt(5) lgkmcnt(6)
	v_mfma_f32_32x32x16_bf16 v[80:95], v[32:35], v[104:107], v[214:229]
	v_mfma_f32_32x32x16_bf16 v[64:79], v[36:39], v[104:107], v[214:229]
	s_waitcnt lgkmcnt(4)
	v_mfma_f32_32x32x16_bf16 v[80:95], v[44:47], v[96:99], v[80:95]
	v_mfma_f32_32x32x16_bf16 v[64:79], v[48:51], v[96:99], v[64:79]
	s_waitcnt lgkmcnt(2)
	v_mfma_f32_32x32x16_bf16 v[80:95], v[52:55], v[100:103], v[80:95]
	v_mfma_f32_32x32x16_bf16 v[64:79], v[56:59], v[100:103], v[64:79]
	s_waitcnt vmcnt(4) lgkmcnt(0)
	v_mfma_f32_32x32x16_bf16 v[80:95], v[60:63], v[108:111], v[80:95]
	v_mfma_f32_32x32x16_bf16 v[64:79], v[146:149], v[108:111], v[64:79]
	s_nop 11
	v_exp_f32_e32 v48, v64
	v_exp_f32_e32 v33, v81
	v_exp_f32_e32 v49, v65
	v_exp_f32_e32 v50, v66
	v_exp_f32_e32 v51, v67
	v_exp_f32_e32 v52, v68
	v_exp_f32_e32 v53, v69
	v_exp_f32_e32 v54, v70
	v_exp_f32_e32 v55, v71
	v_exp_f32_e32 v56, v72
	v_exp_f32_e32 v57, v73
	v_exp_f32_e32 v58, v74
	v_exp_f32_e32 v59, v75
	v_exp_f32_e32 v60, v76
	v_exp_f32_e32 v61, v77
	v_exp_f32_e32 v62, v78
	v_exp_f32_e32 v32, v80
	v_exp_f32_e32 v34, v82
	v_exp_f32_e32 v35, v83
	v_exp_f32_e32 v36, v84
	v_exp_f32_e32 v37, v85
	v_exp_f32_e32 v38, v86
	v_exp_f32_e32 v39, v87
	v_exp_f32_e32 v40, v88
	v_exp_f32_e32 v41, v89
	v_exp_f32_e32 v42, v90
	v_exp_f32_e32 v43, v91
	v_exp_f32_e32 v44, v92
	v_exp_f32_e32 v45, v93
	v_exp_f32_e32 v46, v94
	v_exp_f32_e32 v47, v95
	v_mov_b32_e32 v63, v79
	s_branch .LBB0_384

; #define LAS __attribute__((address_space(3)))
; __device__ __forceinline__ unsigned pk2(float lo, float hi) { f32x2_t v = {lo, hi}; bf16x2_t b = __builtin_convertvector(v, bf16x2_t); return __builtin_bit_cast(unsigned, b); }
; #define MFMA32(a, b, c) __builtin_amdgcn_mfma_f32_32x32x16_bf16((a), (b), (c), 0, 0, 0)
; __device__ __forceinline__ s16x4 vtr(const LAS unsigned char* p) { return __builtin_bit_cast(s16x4, __builtin_amdgcn_ds_read_tr16_b64_v4i16((LAS v4i16_t*)p)); }
; template <int TYPE> __device__ __forceinline__ void attn_unit(const AttnCtx& C, int b, int h, int qb, LAS unsigned char* lds, int tid_in, unsigned* counter) {
;     ...
;                 f32x2_t a2 = {0.f, 0.f};
; #pragma unroll
;                 for (int r = 0; r < 16; r += 2) { a2 += (f32x2_t){p0[r], p0[r + 1]}; a2 += (f32x2_t){p1[r], p1[r + 1]}; }
;                 lsum += a2[0] + a2[1];
;                 bf16x8 pa[4];
; #pragma unroll
;                 for (int s = 0; s < 2; ++s) {
;                     u32x4 a, c2;
;                     a.x = pk2(p0[8 * s + 0], p0[8 * s + 1]); a.y = pk2(p0[8 * s + 2], p0[8 * s + 3]); a.z = pk2(p0[8 * s + 4], p0[8 * s + 5]); a.w = pk2(p0[8 * s + 6], p0[8 * s + 7]);
;                     c2.x = pk2(p1[8 * s + 0], p1[8 * s + 1]); c2.y = pk2(p1[8 * s + 2], p1[8 * s + 3]); c2.z = pk2(p1[8 * s + 4], p1[8 * s + 5]); c2.w = pk2(p1[8 * s + 6], p1[8 * s + 7]);
;                     pa[s] = __builtin_bit_cast(bf16x8, a); pa[2 + s] = __builtin_bit_cast(bf16x8, c2);
;                 }
;                 const LAS unsigned char* vp = Vb + bo + vb0;
; #pragma unroll
;                 for (int dh = 0; dh < 2; ++dh)
; #pragma unroll
;                     for (int ks = 0; ks < 4; ++ks) {
;                         const s16x4 lo = vtr(vp + dh * 4096 + ks * 1024), hh = vtr(vp + dh * 4096 + ks * 1024 + 512);
;                         const bf16x8 vf = {lo[0], lo[1], lo[2], lo[3], hh[0], hh[1], hh[2], hh[3]};
;                         o[dh] = MFMA32(pa[ks], vf, o[dh]);
;                     }
.LBB0_1310:
	v_add_u32_e32 v248, s17, v137
	ds_read_b64_tr_b16 v[232:233], v248 offset:32768
	ds_read_b64_tr_b16 v[234:235], v248 offset:33280
	ds_read_b64_tr_b16 v[236:237], v248 offset:33792
	ds_read_b64_tr_b16 v[238:239], v248 offset:34304
	ds_read_b64_tr_b16 v[240:241], v248 offset:34816
	ds_read_b64_tr_b16 v[242:243], v248 offset:35328
	ds_read_b64_tr_b16 v[244:245], v248 offset:35840
	ds_read_b64_tr_b16 v[246:247], v248 offset:36352
	v_add_u32_e32 v88, s17, v137
	s_nop 0
	v_cvt_pk_bf16_f32 v64, v32, v33
	v_cvt_pk_bf16_f32 v65, v34, v35
	v_cvt_pk_bf16_f32 v66, v36, v37
	v_cvt_pk_bf16_f32 v67, v38, v39
	s_waitcnt lgkmcnt(0)
	s_nop 0
	v_mfma_f32_32x32x16_bf16 v[0:15], v[64:67], v[232:235], v[0:15]
	v_cvt_pk_bf16_f32 v72, v40, v41
	v_cvt_pk_bf16_f32 v73, v42, v43
	v_cvt_pk_bf16_f32 v74, v44, v45
	v_cvt_pk_bf16_f32 v75, v46, v47
	v_cvt_pk_bf16_f32 v68, v48, v49
	v_cvt_pk_bf16_f32 v69, v50, v51
	s_waitcnt lgkmcnt(0)
	v_mfma_f32_32x32x16_bf16 v[0:15], v[72:75], v[236:239], v[0:15]
	v_cvt_pk_bf16_f32 v70, v52, v53
	v_cvt_pk_bf16_f32 v71, v54, v55
	v_exp_f32_e32 v63, v63
	v_cvt_pk_bf16_f32 v80, v56, v57
	v_cvt_pk_bf16_f32 v81, v58, v59
	s_waitcnt lgkmcnt(2)
	v_mfma_f32_32x32x16_bf16 v[0:15], v[68:71], v[240:243], v[0:15]
	ds_read_b64_tr_b16 v[76:77], v88 offset:36864
	ds_read_b64_tr_b16 v[78:79], v88 offset:37376
	v_cvt_pk_bf16_f32 v82, v60, v61
	v_cvt_pk_bf16_f32 v83, v62, v63
	v_add_f32_e64 v32, v32, 0
	v_add_f32_e64 v33, v33, 0
	v_pk_add_f32 v[32:33], v[48:49], v[32:33]
	s_waitcnt lgkmcnt(0)
	v_mfma_f32_32x32x16_bf16 v[16:31], v[64:67], v[76:79], v[16:31]
	v_add_f32_e64 v32, v34, v32
	v_add_f32_e64 v33, v35, v33
	v_add_f32_e64 v32, v50, v32
	v_add_f32_e64 v33, v51, v33
	v_add_f32_e64 v32, v36, v32
	v_add_f32_e64 v33, v37, v33
	v_pk_add_f32 v[32:33], v[52:53], v[32:33]
	v_mfma_f32_32x32x16_bf16 v[0:15], v[80:83], v[244:247], v[0:15]
	ds_read_b64_tr_b16 v[84:85], v88 offset:37888
	ds_read_b64_tr_b16 v[86:87], v88 offset:38400
	v_add_f32_e64 v32, v38, v32
	v_add_f32_e64 v33, v39, v33
	v_add_f32_e64 v32, v54, v32
	v_add_f32_e64 v33, v55, v33
	v_pk_add_f32 v[36:37], v[40:41], v[32:33]
	ds_read_b64_tr_b16 v[32:33], v88 offset:38912
	ds_read_b64_tr_b16 v[34:35], v88 offset:39424
	s_waitcnt lgkmcnt(2)
	v_mfma_f32_32x32x16_bf16 v[16:31], v[72:75], v[84:87], v[16:31]
	v_add_f32_e64 v36, v56, v36
	v_add_f32_e64 v37, v57, v37
	v_add_f32_e64 v40, v42, v36
	v_add_f32_e64 v41, v43, v37
	ds_read_b64_tr_b16 v[36:37], v88 offset:39936
	ds_read_b64_tr_b16 v[38:39], v88 offset:40448
	s_waitcnt lgkmcnt(2)
	v_mfma_f32_32x32x16_bf16 v[16:31], v[68:71], v[32:35], v[16:31]
	v_add_f32_e64 v32, v58, v40
	v_add_f32_e64 v33, v59, v41
	v_add_f32_e64 v32, v44, v32
	v_add_f32_e64 v33, v45, v33
	v_add_f32_e64 v32, v60, v32
	v_add_f32_e64 v33, v61, v33
	v_pk_add_f32 v[32:33], v[46:47], v[32:33]
	s_waitcnt lgkmcnt(0)
	v_mfma_f32_32x32x16_bf16 v[16:31], v[80:83], v[36:39], v[16:31]
	v_add_f32_e64 v32, v62, v32
	v_add_f32_e64 v33, v63, v33
	v_add_f32_e32 v32, v32, v33
	v_add_f32_e32 v138, v138, v32

; #define LAS __attribute__((address_space(3)))
; __device__ __forceinline__ float fast_exp2(float x) { return __builtin_amdgcn_exp2f(x); }
; #define MFMA32(a, b, c) __builtin_amdgcn_mfma_f32_32x32x16_bf16((a), (b), (c), 0, 0, 0)
; template <int TYPE> __device__ __forceinline__ void attn_unit(const AttnCtx& C, int b, int h, int qb, LAS unsigned char* lds, int tid_in, unsigned* counter) {
;     ...
;                 const LAS unsigned char* kp = Kb + bo + hi * 1024 + r32 * 16;
; #pragma unroll
;                 for (int d0 = 0; d0 < 4; ++d0) {
;                     const bf16x8 a0 = *(const LAS bf16x8*)(kp + d0 * 2048), a1 = *(const LAS bf16x8*)(kp + d0 * 2048 + 512);
;                     if (d0 == 0) { p0 = MFMA32(a0, qr[0], (TYPE == 1 ? cvec : zvec)); p1 = MFMA32(a1, qr[0], (TYPE == 1 ? cvec : zvec)); }
;                     else { p0 = MFMA32(a0, qr[d0], p0); p1 = MFMA32(a1, qr[d0], p1); }
;                 }
;     ...
;                     if (cq - t >= 3) { const float bc = relb[256];
; #pragma unroll
;                         for (int r = 0; r < 16; ++r) { p0[r] = fast_exp2(p0[r] + bc); p1[r] = fast_exp2(p1[r] + bc); }
.Lt2far_2:
	v_add_u32_e32 v40, s17, v139
	ds_read_b128 v[32:35], v40
	ds_read_b128 v[36:39], v40 offset:512
	ds_read_b128 v[44:47], v40 offset:2048
	ds_read_b128 v[48:51], v40 offset:2560
	ds_read_b128 v[52:55], v40 offset:4096
	ds_read_b128 v[56:59], v40 offset:4608
	ds_read_b128 v[60:63], v40 offset:6144
	ds_read_b128 v[146:149], v40 offset:6656
	s_waitcnt vmcnt(5) lgkmcnt(6)
	v_mfma_f32_32x32x16_bf16 v[80:95], v[32:35], v[104:107], v[214:229]
	v_mfma_f32_32x32x16_bf16 v[64:79], v[36:39], v[104:107], v[214:229]
	s_waitcnt lgkmcnt(4)
	v_mfma_f32_32x32x16_bf16 v[80:95], v[44:47], v[96:99], v[80:95]
	v_mfma_f32_32x32x16_bf16 v[64:79], v[48:51], v[96:99], v[64:79]
	s_waitcnt lgkmcnt(2)
	v_mfma_f32_32x32x16_bf16 v[80:95], v[52:55], v[100:103], v[80:95]
	v_mfma_f32_32x32x16_bf16 v[64:79], v[56:59], v[100:103], v[64:79]
	s_waitcnt vmcnt(4) lgkmcnt(0)
	v_mfma_f32_32x32x16_bf16 v[80:95], v[60:63], v[108:111], v[80:95]
	v_mfma_f32_32x32x16_bf16 v[64:79], v[146:149], v[108:111], v[64:79]
	s_nop 11
	v_exp_f32_e32 v48, v64
	v_exp_f32_e32 v33, v81
	v_exp_f32_e32 v49, v65
	v_exp_f32_e32 v50, v66
	v_exp_f32_e32 v51, v67
	v_exp_f32_e32 v52, v68
	v_exp_f32_e32 v53, v69
	v_exp_f32_e32 v54, v70
	v_exp_f32_e32 v55, v71
	v_exp_f32_e32 v56, v72
	v_exp_f32_e32 v57, v73
	v_exp_f32_e32 v58, v74
	v_exp_f32_e32 v59, v75
	v_exp_f32_e32 v60, v76
	v_exp_f32_e32 v61, v77
	v_exp_f32_e32 v62, v78
	v_exp_f32_e32 v32, v80
	v_exp_f32_e32 v34, v82
	v_exp_f32_e32 v35, v83
	v_exp_f32_e32 v36, v84
	v_exp_f32_e32 v37, v85
	v_exp_f32_e32 v38, v86
	v_exp_f32_e32 v39, v87
	v_exp_f32_e32 v40, v88
	v_exp_f32_e32 v41, v89
	v_exp_f32_e32 v42, v90
	v_exp_f32_e32 v43, v91
	v_exp_f32_e32 v44, v92
	v_exp_f32_e32 v45, v93
	v_exp_f32_e32 v46, v94
	v_exp_f32_e32 v47, v95
	v_mov_b32_e32 v63, v79
	s_branch .LBB0_1310
